# v81 + in-proj unit loop: wait before the K-loop leaves the previous epilogue's last two stores outstanding (vmcnt(2)); prologue keeps the full wait
# baseline (speedup 1.0000x reference)
; #define PG8_STAGE(bufoff, gbase, voff) do { _Pragma("unroll") for (int _i = 0; _i < 2; ++_i) \
;         __builtin_amdgcn_global_load_lds((const unsigned*)((const char*)(gbase) + (voff)[_i]), (PG8_LAS unsigned*)(lds + (bufoff) + ldsw + _i * 8192), 16, 0, 0); } while (0)
; #define PG8_WAIT_V(n) asm volatile("s_waitcnt vmcnt(" #n ")" ::: "memory")
; #define PG8_BAR __builtin_amdgcn_s_barrier()
; template <class Epi, class Sched, bool ALIGN_EPI = false, bool SP2 = false>
; __device__ __forceinline__ void gemm_phase(PG8_LAS unsigned char* lds, const Gemm g, const Sched& S, const Epi& E) {
;     ...
;     const int tid = tid_, wid = __builtin_amdgcn_readfirstlane(tid >> 6), lane = tid & 63, wr = wid >> 2, wc = wid & 3, fr = lane & 15, fq = lane >> 4;
;     const int K = g.K, nt = K / BK, LD = g.ld;
;     unsigned voffA[2], voffB[2];
; #pragma unroll
;     for (int i = 0; i < 2; ++i) { int R, C; stage_rc(tid * 16 + i * 8192, R, C); const int Rb = Epi::PERM ? ((R & ~31) + perm32(R & 31)) : R;
;         voffA[i] = (unsigned)(R * LD + C) * 2u; voffB[i] = (unsigned)(Rb * LD + C) * 2u; }
;     const size_t kstep = (size_t)(BK * 2);
;     const size_t hstep = (size_t)HALF * LD * 2;
;     const size_t tstep = 2 * hstep;
;     const unsigned ldsw = (unsigned)wid * 1024u;
;     const int aoff = lds_byte(wr * 64 + fr, fq * 8), boff = lds_byte(wc * 32 + fr, fq * 8);
;     ...
;     if constexpr (SP2) {
;         PG8_STAGE(PG8_SB(0, 0), cB, voffB); PG8_STAGE(PG8_SB(0, 1), cB + hstep, voffB); PG8_STAGE(PG8_SA(0, 0), cA, voffA); PG8_STAGE(PG8_SA(0, 1), cA + hstep, voffA);
;         if (wr == 1) PG8_BAR;
;         PG8_WAIT_V(2); PG8_BAR;
;         PG8_STAGE(PG8_SB(1, 0), cB + kstep, voffB); PG8_STAGE(PG8_SA(1, 0), cA + kstep, voffA); PG8_STAGE(PG8_SB(1, 1), cB + hstep + kstep, voffB);
;         PG8_WAIT_V(6); PG8_BAR;
.LBB0_231:
	s_add_u32 s75, s28, 0x200200
	s_addc_u32 s76, s29, 0
	s_add_u32 s44, s28, 0x140000
	s_addc_u32 s45, s29, 0
	s_and_b32 s1, s1, 3
	s_lshl_b32 s5, s4, 13
	s_lshl_b32 s7, s1, 5
	s_lshl_b32 s13, s1, 12
	s_add_u32 s46, s28, 0x30000
	s_mov_b64 s[48:49], 0x80
	s_addc_u32 s47, s29, 0
	s_add_i32 m0, s67, 0x18000
	v_lshl_add_u64 v[6:7], v[6:7], 0, s[48:49]
	s_waitcnt vmcnt(2)
	s_barrier
	global_load_lds_dwordx4 v[6:7], off
	v_lshl_add_u64 v[4:5], v[4:5], 0, s[48:49]
	s_add_i32 m0, s67, 0x1a000
	s_add_i32 s77, s67, 0x8000
	s_add_i32 s78, s67, 0xa000
	global_load_lds_dwordx4 v[4:5], off
	v_lshl_add_u64 v[0:1], v[0:1], 0, s[48:49]
	s_mov_b32 m0, s77
	s_add_u32 s2, s10, 0x80080
	global_load_lds_dwordx4 v[0:1], off
	v_lshl_add_u64 v[0:1], v[2:3], 0, s[48:49]
	s_mov_b32 m0, s78
	s_addc_u32 s3, s11, 0
	global_load_lds_dwordx4 v[0:1], off
	s_add_i32 m0, s67, 0x1c000
	v_lshl_add_u64 v[0:1], s[2:3], 0, v[156:157]
	global_load_lds_dwordx4 v[0:1], off
	v_lshl_add_u64 v[0:1], s[2:3], 0, v[162:163]
	s_add_i32 m0, s67, 0x1e000
	s_cmpk_lt_u32 s0, 0x100
	global_load_lds_dwordx4 v[0:1], off
	v_bfe_u32 v2, v8, 4, 2
	s_cselect_b64 s[50:51], -1, 0
	s_lshl_b32 s0, s4, 12
	v_and_b32_e32 v1, 15, v8
	v_lshlrev_b32_e32 v3, 4, v2
	s_cmp_eq_u32 s1, 0
	v_lshl_or_b32 v153, s4, 6, v1
	v_lshl_or_b32 v4, v1, 6, v3
	v_lshlrev_b32_e32 v1, 2, v1
	s_cselect_b64 s[56:57], -1, 0
	s_add_i32 s4, 0, 0x20000
	v_and_b32_e32 v5, 32, v1
	v_add_u32_e32 v1, s4, v1
	v_lshlrev_b32_e32 v0, 3, v2
	v_cmp_eq_u32_e64 s[2:3], 0, v2
	v_cmp_gt_u32_e32 vcc, 2, v2
	v_lshl_add_u32 v2, s1, 10, v1
	v_add_u32_e32 v206, s0, v1
	v_lshlrev_b32_e32 v1, 15, v9
	v_and_b32_e32 v1, 0xffff0000, v1
	v_and_b32_e32 v205, 16, v3
	v_lshl_add_u32 v1, v10, 12, v1
	v_and_b32_e32 v3, 1, v9
	v_lshl_or_b32 v1, v3, 6, v1
	v_lshl_add_u32 v168, v11, 1, v1
	v_lshlrev_b32_e32 v1, 15, v12
	v_and_b32_e32 v1, 0xffff0000, v1
	s_waitcnt vmcnt(6)
	v_lshl_add_u32 v1, v13, 12, v1
	v_and_b32_e32 v3, 1, v12
	v_bitop3_b32 v6, v4, s5, v5 bitop3:0xde
	v_bitop3_b32 v204, v4, s13, v5 bitop3:0xde
	v_cndmask_b32_e64 v166, 1.0, -1.0, vcc
	v_lshl_or_b32 v1, v3, 6, v1
	s_add_i32 s83, 0, 0x10000
	s_add_i32 s84, 0, 0x14000
	s_ashr_i32 s79, s30, 31
	s_mov_b32 s80, s30
	s_ashr_i32 s81, s12, 31
	v_mov_b32_e32 v167, v166
	v_or_b32_e32 v207, s7, v0
	v_mov_b32_e32 v169, v164
	v_lshl_add_u32 v170, v14, 1, v1
	v_mov_b32_e32 v171, v164
	v_mov_b64_e32 v[172:173], 0x380
	v_mov_b64_e32 v[174:175], 0x37f
	s_movk_i32 s82, 0x71
	v_add_u32_e32 v208, s83, v204
	v_add_u32_e32 v209, s84, v204
	v_add_u32_e32 v210, 0, v6
	s_mov_b32 s85, 0x3d372713
	s_movk_i32 s86, 0x1c00
	s_lshl_b32 s87, s7, 2
	v_lshlrev_b32_e32 v211, 2, v0
	v_mov_b32_e32 v212, 0x358637bd
	s_movk_i32 s88, 0x1f80
	s_movk_i32 s89, 0x1f70
	s_movk_i32 s90, 0x1f60
	s_movk_i32 s91, 0x1f50
	v_mbcnt_hi_u32_b32 v213, -1, v161
	v_add_u32_e32 v214, s0, v2
	v_mov_b32_e32 v215, 0x7cf
	v_mov_b32_e32 v216, 0xfcf
	v_mov_b32_e32 v217, 0x3e0293ee
	v_mov_b32_e32 v218, 0x7df
	v_mov_b32_e32 v219, 0xfdf
	v_mov_b32_e32 v220, 0x7ef
	v_mov_b32_e32 v221, 0xfef
	v_mov_b32_e32 v222, 0x7ff
	v_mov_b32_e32 v223, 0xfff
	s_barrier
	s_waitcnt vmcnt(0)
	s_nop 0
	s_branch .LBB0_234

;     __host__ __device__ bool next(int i, Unit& u) const { if (!StaticOrder::next(i >> 1, u)) return false; u.kh = i & 1; u.slot = i >> 1; return true; }
; template <class Epi, class Sched, bool ALIGN_EPI = false, bool SP2 = false>
; __device__ __forceinline__ void gemm_phase(PG8_LAS unsigned char* lds, const Gemm g, const Sched& S, const Epi& E) {
;     ...
;         const bool has_next = S.next(ui + 1, nxt);
;         const char* nA = has_next ? (const char*)g.A + (size_t)nxt.pm * tstep + nxt.kh * khstep : cA; const char* nB = has_next ? (const char*)g.Bt + (size_t)nxt.pn * tstep + nxt.kh * khstep : cB;
;         for (int t = 0; t < nt; t += 2) {
;             const bool last = (t == nt - 2);
;             const char* a1 = cA + (size_t)(t + 1) * kstep;
;             const char* a2 = last ? nA : cA + (size_t)(t + 2) * kstep; const char* b2 = last ? nB : cB + (size_t)(t + 2) * kstep;
;     ...
; #pragma unroll
;         for (int a = 0; a < 2; ++a)
; #pragma unroll
;             for (int b = 0; b < 2; ++b)
; #pragma unroll
;                 for (int m = 0; m < 4; ++m)
; #pragma unroll
;                     for (int n = 0; n < 2; ++n) acc[a][b][m][n] = (f32x4){0.f, 0.f, 0.f, 0.f};
;         }
;         cur = nxt; cA = nA; cB = nB; ++ui;
.LBB0_236:
	s_ashr_i32 s61, s60, 31
	s_lshl_b64 s[0:1], s[60:61], 20
	s_add_u32 s62, s36, s0
	s_addc_u32 s63, s37, s1
	s_and_b64 s[0:1], s[4:5], exec
	s_cselect_b32 s0, s63, s9
	s_cselect_b32 s1, s62, s8
	s_ashr_i32 s59, s58, 31
	s_lshl_b64 s[64:65], s[58:59], 20
	s_add_u32 s64, s54, s64
	s_addc_u32 s65, s55, s65
	s_and_b64 s[68:69], s[4:5], exec
	s_cselect_b32 s7, s65, s11
	s_cselect_b32 s13, s64, s10
	s_add_u32 s8, s8, 0x80080
	s_addc_u32 s9, s9, 0
	s_add_u32 s59, s10, 0x100
	v_mov_b32_e32 v0, 0
	s_addc_u32 s61, s11, 0
	s_mov_b32 s92, -2
	v_mov_b32_e32 v1, v0
	v_mov_b32_e32 v2, v0
	v_mov_b32_e32 v3, v0
	v_mov_b32_e32 v4, v0
	v_mov_b32_e32 v5, v0
	v_mov_b32_e32 v6, v0
	v_mov_b32_e32 v7, v0
	s_waitcnt vmcnt(2)
	v_mov_b32_e32 v16, v0
	v_mov_b32_e32 v17, v0
	v_mov_b32_e32 v18, v0
	v_mov_b32_e32 v19, v0
	v_mov_b32_e32 v20, v0
	v_mov_b32_e32 v21, v0
	v_mov_b32_e32 v22, v0
	v_mov_b32_e32 v23, v0
	v_mov_b32_e32 v32, v0
	v_mov_b32_e32 v33, v0
	v_mov_b32_e32 v34, v0
	v_mov_b32_e32 v35, v0
	v_mov_b32_e32 v36, v0
	v_mov_b32_e32 v37, v0
	v_mov_b32_e32 v38, v0
	v_mov_b32_e32 v39, v0
	v_mov_b32_e32 v48, v0
	v_mov_b32_e32 v49, v0
	v_mov_b32_e32 v50, v0
	v_mov_b32_e32 v51, v0
	v_mov_b32_e32 v52, v0
	v_mov_b32_e32 v53, v0
	v_mov_b32_e32 v54, v0
	v_mov_b32_e32 v55, v0
	v_mov_b32_e32 v8, v0
	v_mov_b32_e32 v9, v0
	v_mov_b32_e32 v10, v0
	v_mov_b32_e32 v11, v0
	v_mov_b32_e32 v12, v0
	v_mov_b32_e32 v13, v0
	v_mov_b32_e32 v14, v0
	v_mov_b32_e32 v15, v0
	v_mov_b32_e32 v24, v0
	v_mov_b32_e32 v25, v0
	v_mov_b32_e32 v26, v0
	v_mov_b32_e32 v27, v0
	v_mov_b32_e32 v28, v0
	v_mov_b32_e32 v29, v0
	v_mov_b32_e32 v30, v0
	v_mov_b32_e32 v31, v0
	v_mov_b32_e32 v40, v0
	v_mov_b32_e32 v41, v0
	v_mov_b32_e32 v42, v0
	v_mov_b32_e32 v43, v0
	v_mov_b32_e32 v44, v0
	v_mov_b32_e32 v45, v0
	v_mov_b32_e32 v46, v0
	v_mov_b32_e32 v47, v0
	v_mov_b32_e32 v56, v0
	v_mov_b32_e32 v57, v0
	v_mov_b32_e32 v58, v0
	v_mov_b32_e32 v59, v0
	v_mov_b32_e32 v60, v0
	v_mov_b32_e32 v61, v0
	v_mov_b32_e32 v62, v0
	v_mov_b32_e32 v63, v0
	v_mov_b32_e32 v64, v0
	v_mov_b32_e32 v65, v0
	v_mov_b32_e32 v66, v0
	v_mov_b32_e32 v67, v0
	v_mov_b32_e32 v68, v0
	v_mov_b32_e32 v69, v0
	v_mov_b32_e32 v70, v0
	v_mov_b32_e32 v71, v0
	v_mov_b32_e32 v80, v0
	v_mov_b32_e32 v81, v0
	v_mov_b32_e32 v82, v0
	v_mov_b32_e32 v83, v0
	v_mov_b32_e32 v84, v0
	v_mov_b32_e32 v85, v0
	v_mov_b32_e32 v86, v0
	v_mov_b32_e32 v87, v0
	v_mov_b32_e32 v96, v0
	v_mov_b32_e32 v97, v0
	v_mov_b32_e32 v98, v0
	v_mov_b32_e32 v99, v0
	v_mov_b32_e32 v100, v0
	v_mov_b32_e32 v101, v0
	v_mov_b32_e32 v102, v0
	v_mov_b32_e32 v103, v0
	v_mov_b32_e32 v112, v0
	v_mov_b32_e32 v113, v0
	v_mov_b32_e32 v114, v0
	v_mov_b32_e32 v115, v0
	v_mov_b32_e32 v116, v0
	v_mov_b32_e32 v117, v0
	v_mov_b32_e32 v118, v0
	v_mov_b32_e32 v119, v0
	v_mov_b32_e32 v72, v0
	v_mov_b32_e32 v73, v0
	v_mov_b32_e32 v74, v0
	v_mov_b32_e32 v75, v0
	v_mov_b32_e32 v76, v0
	v_mov_b32_e32 v77, v0
	v_mov_b32_e32 v78, v0
	v_mov_b32_e32 v79, v0
	v_mov_b32_e32 v88, v0
	v_mov_b32_e32 v89, v0
	v_mov_b32_e32 v90, v0
	v_mov_b32_e32 v91, v0
	v_mov_b32_e32 v92, v0
	v_mov_b32_e32 v93, v0
	v_mov_b32_e32 v94, v0
	v_mov_b32_e32 v95, v0
	v_mov_b32_e32 v104, v0
	v_mov_b32_e32 v105, v0
	v_mov_b32_e32 v106, v0
	v_mov_b32_e32 v107, v0
	v_mov_b32_e32 v108, v0
	v_mov_b32_e32 v109, v0
	v_mov_b32_e32 v110, v0
	v_mov_b32_e32 v111, v0
	v_mov_b32_e32 v120, v0
	v_mov_b32_e32 v121, v0
	v_mov_b32_e32 v122, v0
	v_mov_b32_e32 v123, v0
	v_mov_b32_e32 v124, v0
	v_mov_b32_e32 v125, v0
	v_mov_b32_e32 v126, v0
	v_mov_b32_e32 v127, v0
